# saddr K-loop with base-pointer bumps moved after the ds_reads in the last load segment
# speedup vs baseline: 1.0221x; 1.0058x over previous
.Lprio_done:
	s_add_u32 s0, s90, 0x80
	s_addc_u32 s1, s91, 0
	s_add_u32 s11, s2, 0x100
	s_addc_u32 s24, s3, 0
	s_mov_b32 s2, 0
	s_add_i32 s90, s2, 2
	s_add_u32 s82, s0, 0x80
	s_addc_u32 s3, s1, 0
	s_add_i32 s83, 0, 0x10000
	s_cmp_eq_u32 s62, s2
	s_cselect_b32 s3, s23, s3
	s_cselect_b32 s2, s22, s82
	s_cselect_b32 vcc_hi, s13, s24
	s_cselect_b32 vcc_lo, s12, s11
	s_add_i32 s82, 0, 0x14000
	v_add_u32_e32 v140, s83, v157
	v_add_u32_e32 v144, s82, v157
	v_add_u32_e32 v232, s26, v150
	v_add_u32_e32 v233, s26, v154
	v_add_u32_e32 v234, s58, v148
	v_add_u32_e32 v235, s58, v152
	ds_read_b128 v[128:131], v140
	ds_read_b128 v[132:135], v140 offset:1024
	ds_read_b128 v[136:139], v140 offset:2048
	ds_read_b128 v[140:143], v140 offset:3072
	ds_read_b128 v[166:169], v144
	ds_read_b128 v[176:179], v144 offset:1024
	ds_read_b128 v[180:183], v144 offset:2048
	ds_read_b128 v[184:187], v144 offset:3072
	s_add_i32 m0, s37, 0xc000
	ds_read_b128 v[188:191], v242
	ds_read_b128 v[192:195], v242 offset:1024
	ds_read_b128 v[196:199], v242 offset:2048
	ds_read_b128 v[200:203], v242 offset:3072
	ds_read_b128 v[204:207], v242 offset:4096
	ds_read_b128 v[208:211], v242 offset:5120
	ds_read_b128 v[212:215], v242 offset:6144
	ds_read_b128 v[216:219], v242 offset:7168
	global_load_lds_dwordx4 v160, s[0:1]
	s_add_i32 m0, s37, 0xe000
	s_nop 0
	global_load_lds_dwordx4 v162, s[0:1]
	s_waitcnt vmcnt(8) lgkmcnt(0)
	s_barrier
	v_mfma_f32_16x16x32_bf16 v[124:127], v[128:131], v[188:191], 0
	v_mfma_f32_16x16x32_bf16 v[120:123], v[136:139], v[188:191], 0
	v_mfma_f32_16x16x32_bf16 v[108:111], v[128:131], v[196:199], 0
	v_mfma_f32_16x16x32_bf16 v[104:107], v[136:139], v[196:199], 0
	v_mfma_f32_16x16x32_bf16 v[92:95], v[128:131], v[204:207], 0
	v_mfma_f32_16x16x32_bf16 v[88:91], v[136:139], v[204:207], 0
	v_mfma_f32_16x16x32_bf16 v[76:79], v[128:131], v[212:215], 0
	v_mfma_f32_16x16x32_bf16 v[72:75], v[136:139], v[212:215], 0
	v_mfma_f32_16x16x32_bf16 v[124:127], v[132:135], v[192:195], v[124:127]
	v_mfma_f32_16x16x32_bf16 v[120:123], v[140:143], v[192:195], v[120:123]
	v_mfma_f32_16x16x32_bf16 v[108:111], v[132:135], v[200:203], v[108:111]
	v_mfma_f32_16x16x32_bf16 v[104:107], v[140:143], v[200:203], v[104:107]
	v_mfma_f32_16x16x32_bf16 v[92:95], v[132:135], v[208:211], v[92:95]
	v_mfma_f32_16x16x32_bf16 v[88:91], v[140:143], v[208:211], v[88:91]
	v_mfma_f32_16x16x32_bf16 v[76:79], v[132:135], v[216:219], v[76:79]
	v_mfma_f32_16x16x32_bf16 v[72:75], v[140:143], v[216:219], v[72:75]
	v_mfma_f32_16x16x32_bf16 v[116:119], v[166:169], v[188:191], 0
	v_mfma_f32_16x16x32_bf16 v[112:115], v[180:183], v[188:191], 0
	v_mfma_f32_16x16x32_bf16 v[100:103], v[166:169], v[196:199], 0
	v_mfma_f32_16x16x32_bf16 v[96:99], v[180:183], v[196:199], 0
	v_mfma_f32_16x16x32_bf16 v[84:87], v[166:169], v[204:207], 0
	v_mfma_f32_16x16x32_bf16 v[80:83], v[180:183], v[204:207], 0
	v_mfma_f32_16x16x32_bf16 v[68:71], v[166:169], v[212:215], 0
	v_mfma_f32_16x16x32_bf16 v[64:67], v[180:183], v[212:215], 0
	v_mfma_f32_16x16x32_bf16 v[116:119], v[176:179], v[192:195], v[116:119]
	v_mfma_f32_16x16x32_bf16 v[112:115], v[184:187], v[192:195], v[112:115]
	v_mfma_f32_16x16x32_bf16 v[100:103], v[176:179], v[200:203], v[100:103]
	v_mfma_f32_16x16x32_bf16 v[96:99], v[184:187], v[200:203], v[96:99]
	v_mfma_f32_16x16x32_bf16 v[84:87], v[176:179], v[208:211], v[84:87]
	v_mfma_f32_16x16x32_bf16 v[80:83], v[184:187], v[208:211], v[80:83]
	v_mfma_f32_16x16x32_bf16 v[68:71], v[176:179], v[216:219], v[68:71]
	v_mfma_f32_16x16x32_bf16 v[64:67], v[184:187], v[216:219], v[64:67]
	s_barrier
	s_add_i32 s83, s83, s36
	s_mov_b32 m0, s83
	ds_read_b128 v[188:191], v242 offset:16384
	ds_read_b128 v[192:195], v242 offset:17408
	ds_read_b128 v[196:199], v242 offset:18432
	ds_read_b128 v[200:203], v242 offset:19456
	ds_read_b128 v[204:207], v242 offset:20480
	ds_read_b128 v[208:211], v242 offset:21504
	ds_read_b128 v[212:215], v242 offset:22528
	ds_read_b128 v[216:219], v242 offset:23552
	global_load_lds_dwordx4 v150, vcc
	s_add_i32 m0, s83, 0x2000
	s_add_i32 s82, s82, s36
	global_load_lds_dwordx4 v154, vcc
	s_mov_b32 m0, s82
	s_nop 0
	global_load_lds_dwordx4 v232, vcc
	s_add_i32 m0, s82, 0x2000
	s_nop 0
	global_load_lds_dwordx4 v233, vcc
	s_mov_b32 m0, s37
	s_nop 0
	global_load_lds_dwordx4 v148, s[2:3]
	s_mov_b32 m0, s42
	s_nop 0
	global_load_lds_dwordx4 v152, s[2:3]
	s_waitcnt vmcnt(8) lgkmcnt(0)
	s_barrier
	v_mfma_f32_16x16x32_bf16 v[60:63], v[128:131], v[188:191], 0
	v_mfma_f32_16x16x32_bf16 v[56:59], v[136:139], v[188:191], 0
	v_mfma_f32_16x16x32_bf16 v[44:47], v[128:131], v[196:199], 0
	v_mfma_f32_16x16x32_bf16 v[40:43], v[136:139], v[196:199], 0
	v_mfma_f32_16x16x32_bf16 v[28:31], v[128:131], v[204:207], 0
	v_mfma_f32_16x16x32_bf16 v[24:27], v[136:139], v[204:207], 0
	v_mfma_f32_16x16x32_bf16 v[12:15], v[128:131], v[212:215], 0
	v_mfma_f32_16x16x32_bf16 v[8:11], v[136:139], v[212:215], 0
	v_mfma_f32_16x16x32_bf16 v[60:63], v[132:135], v[192:195], v[60:63]
	v_mfma_f32_16x16x32_bf16 v[56:59], v[140:143], v[192:195], v[56:59]
	v_mfma_f32_16x16x32_bf16 v[44:47], v[132:135], v[200:203], v[44:47]
	v_mfma_f32_16x16x32_bf16 v[40:43], v[140:143], v[200:203], v[40:43]
	v_mfma_f32_16x16x32_bf16 v[28:31], v[132:135], v[208:211], v[28:31]
	v_mfma_f32_16x16x32_bf16 v[24:27], v[140:143], v[208:211], v[24:27]
	v_mfma_f32_16x16x32_bf16 v[12:15], v[132:135], v[216:219], v[12:15]
	v_mfma_f32_16x16x32_bf16 v[8:11], v[140:143], v[216:219], v[8:11]
	v_mfma_f32_16x16x32_bf16 v[52:55], v[166:169], v[188:191], 0
	v_mfma_f32_16x16x32_bf16 v[48:51], v[180:183], v[188:191], 0
	v_mfma_f32_16x16x32_bf16 v[36:39], v[166:169], v[196:199], 0
	v_mfma_f32_16x16x32_bf16 v[32:35], v[180:183], v[196:199], 0
	v_mfma_f32_16x16x32_bf16 v[20:23], v[166:169], v[204:207], 0
	v_mfma_f32_16x16x32_bf16 v[16:19], v[180:183], v[204:207], 0
	v_mfma_f32_16x16x32_bf16 v[4:7], v[166:169], v[212:215], 0
	v_mfma_f32_16x16x32_bf16 v[0:3], v[180:183], v[212:215], 0
	v_mfma_f32_16x16x32_bf16 v[52:55], v[176:179], v[192:195], v[52:55]
	v_mfma_f32_16x16x32_bf16 v[48:51], v[184:187], v[192:195], v[48:51]
	v_mfma_f32_16x16x32_bf16 v[36:39], v[176:179], v[200:203], v[36:39]
	v_mfma_f32_16x16x32_bf16 v[32:35], v[184:187], v[200:203], v[32:35]
	v_mfma_f32_16x16x32_bf16 v[20:23], v[176:179], v[208:211], v[20:23]
	v_mfma_f32_16x16x32_bf16 v[16:19], v[184:187], v[208:211], v[16:19]
	v_mfma_f32_16x16x32_bf16 v[4:7], v[176:179], v[216:219], v[4:7]
	v_mfma_f32_16x16x32_bf16 v[0:3], v[184:187], v[216:219], v[0:3]
	s_barrier
	s_add_i32 s82, 0, 0x18000
	s_add_i32 s83, 0, 0x1c000
	v_add_u32_e32 v140, s82, v157
	v_add_u32_e32 v144, s83, v157
	ds_read_b128 v[128:131], v140
	ds_read_b128 v[132:135], v140 offset:1024
	ds_read_b128 v[136:139], v140 offset:2048
	ds_read_b128 v[140:143], v140 offset:3072
	ds_read_b128 v[166:169], v144
	ds_read_b128 v[176:179], v144 offset:1024
	ds_read_b128 v[180:183], v144 offset:2048
	ds_read_b128 v[184:187], v144 offset:3072
	s_mov_b32 m0, s43
	ds_read_b128 v[188:191], v242 offset:32768
	ds_read_b128 v[192:195], v242 offset:33792
	ds_read_b128 v[196:199], v242 offset:34816
	ds_read_b128 v[200:203], v242 offset:35840
	ds_read_b128 v[204:207], v242 offset:36864
	ds_read_b128 v[208:211], v242 offset:37888
	ds_read_b128 v[212:215], v242 offset:38912
	ds_read_b128 v[216:219], v242 offset:39936
	global_load_lds_dwordx4 v234, s[2:3]
	s_mov_b32 m0, s16
	s_nop 0
	global_load_lds_dwordx4 v235, s[2:3]
	s_waitcnt vmcnt(8) lgkmcnt(0)
	s_barrier
	v_mfma_f32_16x16x32_bf16 v[124:127], v[128:131], v[188:191], v[124:127]
	v_mfma_f32_16x16x32_bf16 v[120:123], v[136:139], v[188:191], v[120:123]
	v_mfma_f32_16x16x32_bf16 v[108:111], v[128:131], v[196:199], v[108:111]
	v_mfma_f32_16x16x32_bf16 v[104:107], v[136:139], v[196:199], v[104:107]
	v_mfma_f32_16x16x32_bf16 v[92:95], v[128:131], v[204:207], v[92:95]
	v_mfma_f32_16x16x32_bf16 v[88:91], v[136:139], v[204:207], v[88:91]
	v_mfma_f32_16x16x32_bf16 v[76:79], v[128:131], v[212:215], v[76:79]
	v_mfma_f32_16x16x32_bf16 v[72:75], v[136:139], v[212:215], v[72:75]
	v_mfma_f32_16x16x32_bf16 v[124:127], v[132:135], v[192:195], v[124:127]
	v_mfma_f32_16x16x32_bf16 v[120:123], v[140:143], v[192:195], v[120:123]
	v_mfma_f32_16x16x32_bf16 v[108:111], v[132:135], v[200:203], v[108:111]
	v_mfma_f32_16x16x32_bf16 v[104:107], v[140:143], v[200:203], v[104:107]
	v_mfma_f32_16x16x32_bf16 v[92:95], v[132:135], v[208:211], v[92:95]
	v_mfma_f32_16x16x32_bf16 v[88:91], v[140:143], v[208:211], v[88:91]
	v_mfma_f32_16x16x32_bf16 v[76:79], v[132:135], v[216:219], v[76:79]
	v_mfma_f32_16x16x32_bf16 v[72:75], v[140:143], v[216:219], v[72:75]
	v_mfma_f32_16x16x32_bf16 v[116:119], v[166:169], v[188:191], v[116:119]
	v_mfma_f32_16x16x32_bf16 v[112:115], v[180:183], v[188:191], v[112:115]
	v_mfma_f32_16x16x32_bf16 v[100:103], v[166:169], v[196:199], v[100:103]
	v_mfma_f32_16x16x32_bf16 v[96:99], v[180:183], v[196:199], v[96:99]
	v_mfma_f32_16x16x32_bf16 v[84:87], v[166:169], v[204:207], v[84:87]
	v_mfma_f32_16x16x32_bf16 v[80:83], v[180:183], v[204:207], v[80:83]
	v_mfma_f32_16x16x32_bf16 v[68:71], v[166:169], v[212:215], v[68:71]
	v_mfma_f32_16x16x32_bf16 v[64:67], v[180:183], v[212:215], v[64:67]
	v_mfma_f32_16x16x32_bf16 v[116:119], v[176:179], v[192:195], v[116:119]
	v_mfma_f32_16x16x32_bf16 v[112:115], v[184:187], v[192:195], v[112:115]
	v_mfma_f32_16x16x32_bf16 v[100:103], v[176:179], v[200:203], v[100:103]
	v_mfma_f32_16x16x32_bf16 v[96:99], v[184:187], v[200:203], v[96:99]
	v_mfma_f32_16x16x32_bf16 v[84:87], v[176:179], v[208:211], v[84:87]
	v_mfma_f32_16x16x32_bf16 v[80:83], v[184:187], v[208:211], v[80:83]
	v_mfma_f32_16x16x32_bf16 v[68:71], v[176:179], v[216:219], v[68:71]
	v_mfma_f32_16x16x32_bf16 v[64:67], v[184:187], v[216:219], v[64:67]
	s_barrier
	s_add_i32 m0, s82, s36
	ds_read_b128 v[188:191], v242 offset:49152
	ds_read_b128 v[192:195], v242 offset:50176
	ds_read_b128 v[196:199], v242 offset:51200
	ds_read_b128 v[200:203], v242 offset:52224
	ds_read_b128 v[204:207], v242 offset:53248
	ds_read_b128 v[208:211], v242 offset:54272
	ds_read_b128 v[212:215], v242 offset:55296
	ds_read_b128 v[216:219], v242 offset:56320
	s_add_u32 vcc_lo, vcc_lo, 0x80
	s_addc_u32 vcc_hi, vcc_hi, 0
	global_load_lds_dwordx4 v150, vcc
	s_add_i32 m0, m0, 0x2000
	s_add_u32 s2, s2, 0x80
	s_addc_u32 s3, s3, 0
	global_load_lds_dwordx4 v154, vcc
	s_add_i32 m0, s83, s36
	s_nop 0
	global_load_lds_dwordx4 v232, vcc
	s_add_i32 m0, m0, 0x2000
	s_nop 0
	global_load_lds_dwordx4 v233, vcc
	s_mov_b32 m0, s63
	s_nop 0
	global_load_lds_dwordx4 v148, s[2:3]
	s_mov_b32 m0, s18
	s_nop 0
	global_load_lds_dwordx4 v152, s[2:3]
	s_waitcnt vmcnt(8) lgkmcnt(0)
	s_barrier
	v_mfma_f32_16x16x32_bf16 v[60:63], v[128:131], v[188:191], v[60:63]
	v_mfma_f32_16x16x32_bf16 v[56:59], v[136:139], v[188:191], v[56:59]
	v_mfma_f32_16x16x32_bf16 v[44:47], v[128:131], v[196:199], v[44:47]
	v_mfma_f32_16x16x32_bf16 v[40:43], v[136:139], v[196:199], v[40:43]
	v_mfma_f32_16x16x32_bf16 v[28:31], v[128:131], v[204:207], v[28:31]
	v_mfma_f32_16x16x32_bf16 v[24:27], v[136:139], v[204:207], v[24:27]
	v_mfma_f32_16x16x32_bf16 v[12:15], v[128:131], v[212:215], v[12:15]
	v_mfma_f32_16x16x32_bf16 v[8:11], v[136:139], v[212:215], v[8:11]
	v_mfma_f32_16x16x32_bf16 v[60:63], v[132:135], v[192:195], v[60:63]
	v_mfma_f32_16x16x32_bf16 v[56:59], v[140:143], v[192:195], v[56:59]
	v_mfma_f32_16x16x32_bf16 v[44:47], v[132:135], v[200:203], v[44:47]
	v_mfma_f32_16x16x32_bf16 v[40:43], v[140:143], v[200:203], v[40:43]
	v_mfma_f32_16x16x32_bf16 v[28:31], v[132:135], v[208:211], v[28:31]
	v_mfma_f32_16x16x32_bf16 v[24:27], v[140:143], v[208:211], v[24:27]
	v_mfma_f32_16x16x32_bf16 v[12:15], v[132:135], v[216:219], v[12:15]
	v_mfma_f32_16x16x32_bf16 v[8:11], v[140:143], v[216:219], v[8:11]
	v_mfma_f32_16x16x32_bf16 v[52:55], v[166:169], v[188:191], v[52:55]
	v_mfma_f32_16x16x32_bf16 v[48:51], v[180:183], v[188:191], v[48:51]
	v_mfma_f32_16x16x32_bf16 v[36:39], v[166:169], v[196:199], v[36:39]
	v_mfma_f32_16x16x32_bf16 v[32:35], v[180:183], v[196:199], v[32:35]
	v_mfma_f32_16x16x32_bf16 v[20:23], v[166:169], v[204:207], v[20:23]
	v_mfma_f32_16x16x32_bf16 v[16:19], v[180:183], v[204:207], v[16:19]
	v_mfma_f32_16x16x32_bf16 v[4:7], v[166:169], v[212:215], v[4:7]
	v_mfma_f32_16x16x32_bf16 v[0:3], v[180:183], v[212:215], v[0:3]
	v_mfma_f32_16x16x32_bf16 v[52:55], v[176:179], v[192:195], v[52:55]
	v_mfma_f32_16x16x32_bf16 v[48:51], v[184:187], v[192:195], v[48:51]
	v_mfma_f32_16x16x32_bf16 v[36:39], v[176:179], v[200:203], v[36:39]
	v_mfma_f32_16x16x32_bf16 v[32:35], v[184:187], v[200:203], v[32:35]
	v_mfma_f32_16x16x32_bf16 v[20:23], v[176:179], v[208:211], v[20:23]
	v_mfma_f32_16x16x32_bf16 v[16:19], v[184:187], v[208:211], v[16:19]
	v_mfma_f32_16x16x32_bf16 v[4:7], v[176:179], v[216:219], v[4:7]
	v_mfma_f32_16x16x32_bf16 v[0:3], v[184:187], v[216:219], v[0:3]
	s_barrier
	s_add_u32 s0, s0, 0x100
	s_addc_u32 s1, s1, 0
	s_add_u32 s11, s11, 0x100
	s_addc_u32 s24, s24, 0
	s_cmp_ge_u32 s90, s60
	s_mov_b32 s2, s90
	s_cbranch_scc1 .LBB0_297
.LBB0_295:
	s_add_i32 s90, s2, 2
	s_add_u32 s82, s0, 0x80
	s_addc_u32 s3, s1, 0
	s_add_i32 s83, 0, 0x10000
	s_cmp_eq_u32 s62, s2
	s_cselect_b32 s3, s23, s3
	s_cselect_b32 s2, s22, s82
	s_cselect_b32 vcc_hi, s13, s24
	s_cselect_b32 vcc_lo, s12, s11
	s_add_i32 s82, 0, 0x14000
	v_add_u32_e32 v140, s83, v157
	v_add_u32_e32 v144, s82, v157
	ds_read_b128 v[128:131], v140
	ds_read_b128 v[132:135], v140 offset:1024
	ds_read_b128 v[136:139], v140 offset:2048
	ds_read_b128 v[140:143], v140 offset:3072
	ds_read_b128 v[166:169], v144
	ds_read_b128 v[176:179], v144 offset:1024
	ds_read_b128 v[180:183], v144 offset:2048
	ds_read_b128 v[184:187], v144 offset:3072
	s_add_i32 m0, s37, 0xc000
	ds_read_b128 v[188:191], v242
	ds_read_b128 v[192:195], v242 offset:1024
	ds_read_b128 v[196:199], v242 offset:2048
	ds_read_b128 v[200:203], v242 offset:3072
	ds_read_b128 v[204:207], v242 offset:4096
	ds_read_b128 v[208:211], v242 offset:5120
	ds_read_b128 v[212:215], v242 offset:6144
	ds_read_b128 v[216:219], v242 offset:7168
	global_load_lds_dwordx4 v160, s[0:1]
	s_add_i32 m0, s37, 0xe000
	s_nop 0
	global_load_lds_dwordx4 v162, s[0:1]
	s_waitcnt vmcnt(8) lgkmcnt(0)
	s_barrier
	v_mfma_f32_16x16x32_bf16 v[124:127], v[128:131], v[188:191], v[124:127]
	v_mfma_f32_16x16x32_bf16 v[120:123], v[136:139], v[188:191], v[120:123]
	v_mfma_f32_16x16x32_bf16 v[108:111], v[128:131], v[196:199], v[108:111]
	v_mfma_f32_16x16x32_bf16 v[104:107], v[136:139], v[196:199], v[104:107]
	v_mfma_f32_16x16x32_bf16 v[92:95], v[128:131], v[204:207], v[92:95]
	v_mfma_f32_16x16x32_bf16 v[88:91], v[136:139], v[204:207], v[88:91]
	v_mfma_f32_16x16x32_bf16 v[76:79], v[128:131], v[212:215], v[76:79]
	v_mfma_f32_16x16x32_bf16 v[72:75], v[136:139], v[212:215], v[72:75]
	v_mfma_f32_16x16x32_bf16 v[124:127], v[132:135], v[192:195], v[124:127]
	v_mfma_f32_16x16x32_bf16 v[120:123], v[140:143], v[192:195], v[120:123]
	v_mfma_f32_16x16x32_bf16 v[108:111], v[132:135], v[200:203], v[108:111]
	v_mfma_f32_16x16x32_bf16 v[104:107], v[140:143], v[200:203], v[104:107]
	v_mfma_f32_16x16x32_bf16 v[92:95], v[132:135], v[208:211], v[92:95]
	v_mfma_f32_16x16x32_bf16 v[88:91], v[140:143], v[208:211], v[88:91]
	v_mfma_f32_16x16x32_bf16 v[76:79], v[132:135], v[216:219], v[76:79]
	v_mfma_f32_16x16x32_bf16 v[72:75], v[140:143], v[216:219], v[72:75]
	v_mfma_f32_16x16x32_bf16 v[116:119], v[166:169], v[188:191], v[116:119]
	v_mfma_f32_16x16x32_bf16 v[112:115], v[180:183], v[188:191], v[112:115]
	v_mfma_f32_16x16x32_bf16 v[100:103], v[166:169], v[196:199], v[100:103]
	v_mfma_f32_16x16x32_bf16 v[96:99], v[180:183], v[196:199], v[96:99]
	v_mfma_f32_16x16x32_bf16 v[84:87], v[166:169], v[204:207], v[84:87]
	v_mfma_f32_16x16x32_bf16 v[80:83], v[180:183], v[204:207], v[80:83]
	v_mfma_f32_16x16x32_bf16 v[68:71], v[166:169], v[212:215], v[68:71]
	v_mfma_f32_16x16x32_bf16 v[64:67], v[180:183], v[212:215], v[64:67]
	v_mfma_f32_16x16x32_bf16 v[116:119], v[176:179], v[192:195], v[116:119]
	v_mfma_f32_16x16x32_bf16 v[112:115], v[184:187], v[192:195], v[112:115]
	v_mfma_f32_16x16x32_bf16 v[100:103], v[176:179], v[200:203], v[100:103]
	v_mfma_f32_16x16x32_bf16 v[96:99], v[184:187], v[200:203], v[96:99]
	v_mfma_f32_16x16x32_bf16 v[84:87], v[176:179], v[208:211], v[84:87]
	v_mfma_f32_16x16x32_bf16 v[80:83], v[184:187], v[208:211], v[80:83]
	v_mfma_f32_16x16x32_bf16 v[68:71], v[176:179], v[216:219], v[68:71]
	v_mfma_f32_16x16x32_bf16 v[64:67], v[184:187], v[216:219], v[64:67]
	s_barrier
	s_add_i32 s83, s83, s36
	s_mov_b32 m0, s83
	ds_read_b128 v[188:191], v242 offset:16384
	ds_read_b128 v[192:195], v242 offset:17408
	ds_read_b128 v[196:199], v242 offset:18432
	ds_read_b128 v[200:203], v242 offset:19456
	ds_read_b128 v[204:207], v242 offset:20480
	ds_read_b128 v[208:211], v242 offset:21504
	ds_read_b128 v[212:215], v242 offset:22528
	ds_read_b128 v[216:219], v242 offset:23552
	global_load_lds_dwordx4 v150, vcc
	s_add_i32 m0, s83, 0x2000
	s_add_i32 s82, s82, s36
	global_load_lds_dwordx4 v154, vcc
	s_mov_b32 m0, s82
	s_nop 0
	global_load_lds_dwordx4 v232, vcc
	s_add_i32 m0, s82, 0x2000
	s_nop 0
	global_load_lds_dwordx4 v233, vcc
	s_mov_b32 m0, s37
	s_nop 0
	global_load_lds_dwordx4 v148, s[2:3]
	s_mov_b32 m0, s42
	s_nop 0
	global_load_lds_dwordx4 v152, s[2:3]
	s_waitcnt vmcnt(8) lgkmcnt(0)
	s_barrier
	v_mfma_f32_16x16x32_bf16 v[60:63], v[128:131], v[188:191], v[60:63]
	v_mfma_f32_16x16x32_bf16 v[56:59], v[136:139], v[188:191], v[56:59]
	v_mfma_f32_16x16x32_bf16 v[44:47], v[128:131], v[196:199], v[44:47]
	v_mfma_f32_16x16x32_bf16 v[40:43], v[136:139], v[196:199], v[40:43]
	v_mfma_f32_16x16x32_bf16 v[28:31], v[128:131], v[204:207], v[28:31]
	v_mfma_f32_16x16x32_bf16 v[24:27], v[136:139], v[204:207], v[24:27]
	v_mfma_f32_16x16x32_bf16 v[12:15], v[128:131], v[212:215], v[12:15]
	v_mfma_f32_16x16x32_bf16 v[8:11], v[136:139], v[212:215], v[8:11]
	v_mfma_f32_16x16x32_bf16 v[60:63], v[132:135], v[192:195], v[60:63]
	v_mfma_f32_16x16x32_bf16 v[56:59], v[140:143], v[192:195], v[56:59]
	v_mfma_f32_16x16x32_bf16 v[44:47], v[132:135], v[200:203], v[44:47]
	v_mfma_f32_16x16x32_bf16 v[40:43], v[140:143], v[200:203], v[40:43]
	v_mfma_f32_16x16x32_bf16 v[28:31], v[132:135], v[208:211], v[28:31]
	v_mfma_f32_16x16x32_bf16 v[24:27], v[140:143], v[208:211], v[24:27]
	v_mfma_f32_16x16x32_bf16 v[12:15], v[132:135], v[216:219], v[12:15]
	v_mfma_f32_16x16x32_bf16 v[8:11], v[140:143], v[216:219], v[8:11]
	v_mfma_f32_16x16x32_bf16 v[52:55], v[166:169], v[188:191], v[52:55]
	v_mfma_f32_16x16x32_bf16 v[48:51], v[180:183], v[188:191], v[48:51]
	v_mfma_f32_16x16x32_bf16 v[36:39], v[166:169], v[196:199], v[36:39]
	v_mfma_f32_16x16x32_bf16 v[32:35], v[180:183], v[196:199], v[32:35]
	v_mfma_f32_16x16x32_bf16 v[20:23], v[166:169], v[204:207], v[20:23]
	v_mfma_f32_16x16x32_bf16 v[16:19], v[180:183], v[204:207], v[16:19]
	v_mfma_f32_16x16x32_bf16 v[4:7], v[166:169], v[212:215], v[4:7]
	v_mfma_f32_16x16x32_bf16 v[0:3], v[180:183], v[212:215], v[0:3]
	v_mfma_f32_16x16x32_bf16 v[52:55], v[176:179], v[192:195], v[52:55]
	v_mfma_f32_16x16x32_bf16 v[48:51], v[184:187], v[192:195], v[48:51]
	v_mfma_f32_16x16x32_bf16 v[36:39], v[176:179], v[200:203], v[36:39]
	v_mfma_f32_16x16x32_bf16 v[32:35], v[184:187], v[200:203], v[32:35]
	v_mfma_f32_16x16x32_bf16 v[20:23], v[176:179], v[208:211], v[20:23]
	v_mfma_f32_16x16x32_bf16 v[16:19], v[184:187], v[208:211], v[16:19]
	v_mfma_f32_16x16x32_bf16 v[4:7], v[176:179], v[216:219], v[4:7]
	v_mfma_f32_16x16x32_bf16 v[0:3], v[184:187], v[216:219], v[0:3]
	s_barrier
	s_add_i32 s82, 0, 0x18000
	s_add_i32 s83, 0, 0x1c000
	v_add_u32_e32 v140, s82, v157
	v_add_u32_e32 v144, s83, v157
	ds_read_b128 v[128:131], v140
	ds_read_b128 v[132:135], v140 offset:1024
	ds_read_b128 v[136:139], v140 offset:2048
	ds_read_b128 v[140:143], v140 offset:3072
	ds_read_b128 v[166:169], v144
	ds_read_b128 v[176:179], v144 offset:1024
	ds_read_b128 v[180:183], v144 offset:2048
	ds_read_b128 v[184:187], v144 offset:3072
	s_mov_b32 m0, s43
	ds_read_b128 v[188:191], v242 offset:32768
	ds_read_b128 v[192:195], v242 offset:33792
	ds_read_b128 v[196:199], v242 offset:34816
	ds_read_b128 v[200:203], v242 offset:35840
	ds_read_b128 v[204:207], v242 offset:36864
	ds_read_b128 v[208:211], v242 offset:37888
	ds_read_b128 v[212:215], v242 offset:38912
	ds_read_b128 v[216:219], v242 offset:39936
	global_load_lds_dwordx4 v234, s[2:3]
	s_mov_b32 m0, s16
	s_nop 0
	global_load_lds_dwordx4 v235, s[2:3]
	s_waitcnt vmcnt(8) lgkmcnt(0)
	s_barrier
	v_mfma_f32_16x16x32_bf16 v[124:127], v[128:131], v[188:191], v[124:127]
	v_mfma_f32_16x16x32_bf16 v[120:123], v[136:139], v[188:191], v[120:123]
	v_mfma_f32_16x16x32_bf16 v[108:111], v[128:131], v[196:199], v[108:111]
	v_mfma_f32_16x16x32_bf16 v[104:107], v[136:139], v[196:199], v[104:107]
	v_mfma_f32_16x16x32_bf16 v[92:95], v[128:131], v[204:207], v[92:95]
	v_mfma_f32_16x16x32_bf16 v[88:91], v[136:139], v[204:207], v[88:91]
	v_mfma_f32_16x16x32_bf16 v[76:79], v[128:131], v[212:215], v[76:79]
	v_mfma_f32_16x16x32_bf16 v[72:75], v[136:139], v[212:215], v[72:75]
	v_mfma_f32_16x16x32_bf16 v[124:127], v[132:135], v[192:195], v[124:127]
	v_mfma_f32_16x16x32_bf16 v[120:123], v[140:143], v[192:195], v[120:123]
	v_mfma_f32_16x16x32_bf16 v[108:111], v[132:135], v[200:203], v[108:111]
	v_mfma_f32_16x16x32_bf16 v[104:107], v[140:143], v[200:203], v[104:107]
	v_mfma_f32_16x16x32_bf16 v[92:95], v[132:135], v[208:211], v[92:95]
	v_mfma_f32_16x16x32_bf16 v[88:91], v[140:143], v[208:211], v[88:91]
	v_mfma_f32_16x16x32_bf16 v[76:79], v[132:135], v[216:219], v[76:79]
	v_mfma_f32_16x16x32_bf16 v[72:75], v[140:143], v[216:219], v[72:75]
	v_mfma_f32_16x16x32_bf16 v[116:119], v[166:169], v[188:191], v[116:119]
	v_mfma_f32_16x16x32_bf16 v[112:115], v[180:183], v[188:191], v[112:115]
	v_mfma_f32_16x16x32_bf16 v[100:103], v[166:169], v[196:199], v[100:103]
	v_mfma_f32_16x16x32_bf16 v[96:99], v[180:183], v[196:199], v[96:99]
	v_mfma_f32_16x16x32_bf16 v[84:87], v[166:169], v[204:207], v[84:87]
	v_mfma_f32_16x16x32_bf16 v[80:83], v[180:183], v[204:207], v[80:83]
	v_mfma_f32_16x16x32_bf16 v[68:71], v[166:169], v[212:215], v[68:71]
	v_mfma_f32_16x16x32_bf16 v[64:67], v[180:183], v[212:215], v[64:67]
	v_mfma_f32_16x16x32_bf16 v[116:119], v[176:179], v[192:195], v[116:119]
	v_mfma_f32_16x16x32_bf16 v[112:115], v[184:187], v[192:195], v[112:115]
	v_mfma_f32_16x16x32_bf16 v[100:103], v[176:179], v[200:203], v[100:103]
	v_mfma_f32_16x16x32_bf16 v[96:99], v[184:187], v[200:203], v[96:99]
	v_mfma_f32_16x16x32_bf16 v[84:87], v[176:179], v[208:211], v[84:87]
	v_mfma_f32_16x16x32_bf16 v[80:83], v[184:187], v[208:211], v[80:83]
	v_mfma_f32_16x16x32_bf16 v[68:71], v[176:179], v[216:219], v[68:71]
	v_mfma_f32_16x16x32_bf16 v[64:67], v[184:187], v[216:219], v[64:67]
	s_barrier
	s_add_i32 m0, s82, s36
	ds_read_b128 v[188:191], v242 offset:49152
	ds_read_b128 v[192:195], v242 offset:50176
	ds_read_b128 v[196:199], v242 offset:51200
	ds_read_b128 v[200:203], v242 offset:52224
	ds_read_b128 v[204:207], v242 offset:53248
	ds_read_b128 v[208:211], v242 offset:54272
	ds_read_b128 v[212:215], v242 offset:55296
	ds_read_b128 v[216:219], v242 offset:56320
	s_add_u32 vcc_lo, vcc_lo, 0x80
	s_addc_u32 vcc_hi, vcc_hi, 0
	global_load_lds_dwordx4 v150, vcc
	s_add_i32 m0, m0, 0x2000
	s_add_u32 s2, s2, 0x80
	s_addc_u32 s3, s3, 0
	global_load_lds_dwordx4 v154, vcc
	s_add_i32 m0, s83, s36
	s_nop 0
	global_load_lds_dwordx4 v232, vcc
	s_add_i32 m0, m0, 0x2000
	s_nop 0
	global_load_lds_dwordx4 v233, vcc
	s_mov_b32 m0, s63
	s_nop 0
	global_load_lds_dwordx4 v148, s[2:3]
	s_mov_b32 m0, s18
	s_nop 0
	global_load_lds_dwordx4 v152, s[2:3]
	s_waitcnt vmcnt(8) lgkmcnt(0)
	s_barrier
	v_mfma_f32_16x16x32_bf16 v[60:63], v[128:131], v[188:191], v[60:63]
	v_mfma_f32_16x16x32_bf16 v[56:59], v[136:139], v[188:191], v[56:59]
	v_mfma_f32_16x16x32_bf16 v[44:47], v[128:131], v[196:199], v[44:47]
	v_mfma_f32_16x16x32_bf16 v[40:43], v[136:139], v[196:199], v[40:43]
	v_mfma_f32_16x16x32_bf16 v[28:31], v[128:131], v[204:207], v[28:31]
	v_mfma_f32_16x16x32_bf16 v[24:27], v[136:139], v[204:207], v[24:27]
	v_mfma_f32_16x16x32_bf16 v[12:15], v[128:131], v[212:215], v[12:15]
	v_mfma_f32_16x16x32_bf16 v[8:11], v[136:139], v[212:215], v[8:11]
	v_mfma_f32_16x16x32_bf16 v[60:63], v[132:135], v[192:195], v[60:63]
	v_mfma_f32_16x16x32_bf16 v[56:59], v[140:143], v[192:195], v[56:59]
	v_mfma_f32_16x16x32_bf16 v[44:47], v[132:135], v[200:203], v[44:47]
	v_mfma_f32_16x16x32_bf16 v[40:43], v[140:143], v[200:203], v[40:43]
	v_mfma_f32_16x16x32_bf16 v[28:31], v[132:135], v[208:211], v[28:31]
	v_mfma_f32_16x16x32_bf16 v[24:27], v[140:143], v[208:211], v[24:27]
	v_mfma_f32_16x16x32_bf16 v[12:15], v[132:135], v[216:219], v[12:15]
	v_mfma_f32_16x16x32_bf16 v[8:11], v[140:143], v[216:219], v[8:11]
	v_mfma_f32_16x16x32_bf16 v[52:55], v[166:169], v[188:191], v[52:55]
	v_mfma_f32_16x16x32_bf16 v[48:51], v[180:183], v[188:191], v[48:51]
	v_mfma_f32_16x16x32_bf16 v[36:39], v[166:169], v[196:199], v[36:39]
	v_mfma_f32_16x16x32_bf16 v[32:35], v[180:183], v[196:199], v[32:35]
	v_mfma_f32_16x16x32_bf16 v[20:23], v[166:169], v[204:207], v[20:23]
	v_mfma_f32_16x16x32_bf16 v[16:19], v[180:183], v[204:207], v[16:19]
	v_mfma_f32_16x16x32_bf16 v[4:7], v[166:169], v[212:215], v[4:7]
	v_mfma_f32_16x16x32_bf16 v[0:3], v[180:183], v[212:215], v[0:3]
	v_mfma_f32_16x16x32_bf16 v[52:55], v[176:179], v[192:195], v[52:55]
	v_mfma_f32_16x16x32_bf16 v[48:51], v[184:187], v[192:195], v[48:51]
	v_mfma_f32_16x16x32_bf16 v[36:39], v[176:179], v[200:203], v[36:39]
	v_mfma_f32_16x16x32_bf16 v[32:35], v[184:187], v[200:203], v[32:35]
	v_mfma_f32_16x16x32_bf16 v[20:23], v[176:179], v[208:211], v[20:23]
	v_mfma_f32_16x16x32_bf16 v[16:19], v[184:187], v[208:211], v[16:19]
	v_mfma_f32_16x16x32_bf16 v[4:7], v[176:179], v[216:219], v[4:7]
	v_mfma_f32_16x16x32_bf16 v[0:3], v[184:187], v[216:219], v[0:3]
	s_barrier
	s_add_u32 s0, s0, 0x100
	s_addc_u32 s1, s1, 0
	s_add_u32 s11, s11, 0x100
	s_addc_u32 s24, s24, 0
	s_cmp_ge_u32 s90, s60
	s_mov_b32 s2, s90
	s_cbranch_scc0 .LBB0_295
	s_branch .LBB0_297
